# CV1/CV2 weights read once chip-wide (4 rows x 16 batches per wave), sc1 result stores, per-WG arrive on per-island counters, wave-0 check of 8 counters at P5 entry
# speedup vs baseline: 1.0189x; 1.0189x over previous
.Lsplit1_got:
	s_waitcnt lgkmcnt(0)
	buffer_inv sc1
	s_waitcnt vmcnt(0)
	v_readlane_b32 s2, v254, 8
	v_readlane_b32 s3, v254, 9
	v_readlane_b32 s4, v254, 20
	v_mov_b32_e32 v16, 0
	v_mov_b32_e32 v17, 1
	s_and_b32 s4, s4, 7
	s_lshl_b32 s4, s4, 8
	s_add_u32 s2, s2, s4
	s_addc_u32 s3, s3, 0
	global_atomic_add v16, v17, s[2:3] offset:2176
	s_branch .LBB0_529
.Lsplit1_full:
	v_readlane_b32 s2, v254, 8
	v_readlane_b32 s3, v254, 9
	v_readlane_b32 s4, v254, 20
	v_mov_b32_e32 v16, 0
	v_mov_b32_e32 v17, 1
	s_and_b32 s4, s4, 7
	s_lshl_b32 s4, s4, 8
	s_add_u32 s2, s2, s4
	s_addc_u32 s3, s3, 0
	global_atomic_add v16, v17, s[2:3] offset:2176
	s_mov_b64 s[4:5], exec
	s_lshl_b32 s2, s68, 8
	v_mbcnt_lo_u32_b32 v1, s4, 0
	s_add_u32 s2, s66, s2
	v_mbcnt_hi_u32_b32 v1, s5, v1
	s_addc_u32 s3, s67, 0
	v_cmp_eq_u32_e32 vcc, 0, v1
	s_and_saveexec_b64 s[8:9], vcc
	s_cbranch_execz .LBB0_495
	s_bcnt1_i32_b64 s4, s[4:5]
	v_mov_b32_e32 v3, 0x1000
	v_mov_b32_e32 v4, s4
	global_atomic_add v3, v3, v4, s[2:3] offset:1024 sc0

.LBB0_642:
	v_mbcnt_lo_u32_b32 v0, -1, 0
	v_mbcnt_hi_u32_b32 v0, -1, v0
	s_waitcnt vmcnt(0)
	s_waitcnt lgkmcnt(0)
	v_or_b32_e32 v0, s89, v0
	v_cmp_eq_u32_e32 vcc, 0, v0
	s_barrier
	s_and_saveexec_b64 s[0:1], vcc
	s_xor_b64 s[0:1], exec, s[0:1]
	s_cbranch_execz .LBB0_695
	v_readlane_b32 s2, v254, 8
	v_readlane_b32 s3, v254, 9
	v_mov_b32_e32 v18, 0
	s_nop 3
	global_load_dword v20, v18, s[2:3] offset:2176 sc1
	global_load_dword v21, v18, s[2:3] offset:2432 sc1
	global_load_dword v22, v18, s[2:3] offset:2688 sc1
	global_load_dword v23, v18, s[2:3] offset:2944 sc1
	global_load_dword v24, v18, s[2:3] offset:3200 sc1
	global_load_dword v25, v18, s[2:3] offset:3456 sc1
	global_load_dword v26, v18, s[2:3] offset:3712 sc1
	global_load_dword v27, v18, s[2:3] offset:3968 sc1
	s_add_i32 s2, 0, 0x22028
	v_mov_b32_e32 v0, s2
	s_waitcnt vmcnt(0) expcnt(0) lgkmcnt(0)
	ds_read_b32 v2, v0
	s_add_i32 s2, 0, 0x2202c
	v_mov_b32_e32 v0, s2
	ds_read_b32 v0, v0
	s_waitcnt lgkmcnt(1)
	v_cmp_ne_u32_e32 vcc, 0, v2
	s_cbranch_vccnz .LBB0_658
	s_add_u32 s2, s66, 0x1000
	s_addc_u32 s3, s67, 0
	s_add_u32 s4, s66, 0x1100
	s_addc_u32 s5, s67, 0
	s_add_u32 s6, s66, 0x1200
	s_addc_u32 s7, s67, 0
	s_add_u32 s8, s66, 0x1300
	s_addc_u32 s9, s67, 0
	s_mov_b32 s10, 1
	v_mov_b32_e32 v16, 0
	s_branch .LBB0_646

.LBB0_695:
	s_or_b64 exec, exec, s[0:1]
	v_readlane_b32 s2, v254, 25
	s_cmp_lg_u32 s2, 0
	s_cbranch_scc1 .Lgcv_done
	s_waitcnt vmcnt(0)
	v_readfirstlane_b32 s4, v20
	v_readfirstlane_b32 s5, v21
	s_min_u32 s4, s4, s5
	v_readfirstlane_b32 s5, v22
	s_min_u32 s4, s4, s5
	v_readfirstlane_b32 s5, v23
	s_min_u32 s4, s4, s5
	v_readfirstlane_b32 s5, v24
	s_min_u32 s4, s4, s5
	v_readfirstlane_b32 s5, v25
	s_min_u32 s4, s4, s5
	v_readfirstlane_b32 s5, v26
	s_min_u32 s4, s4, s5
	v_readfirstlane_b32 s5, v27
	s_min_u32 s4, s4, s5
	s_cmp_lt_u32 s4, 32
	s_cbranch_scc0 .Lgcv_ok
	v_readlane_b32 s2, v254, 8
	v_readlane_b32 s3, v254, 9
	v_mov_b32_e32 v18, 0
	s_nop 3
.Lgcv_poll:
	global_load_dword v20, v18, s[2:3] offset:2176 sc1
	global_load_dword v21, v18, s[2:3] offset:2432 sc1
	global_load_dword v22, v18, s[2:3] offset:2688 sc1
	global_load_dword v23, v18, s[2:3] offset:2944 sc1
	global_load_dword v24, v18, s[2:3] offset:3200 sc1
	global_load_dword v25, v18, s[2:3] offset:3456 sc1
	global_load_dword v26, v18, s[2:3] offset:3712 sc1
	global_load_dword v27, v18, s[2:3] offset:3968 sc1
	s_waitcnt vmcnt(0)
	v_readfirstlane_b32 s4, v20
	v_readfirstlane_b32 s5, v21
	s_min_u32 s4, s4, s5
	v_readfirstlane_b32 s5, v22
	s_min_u32 s4, s4, s5
	v_readfirstlane_b32 s5, v23
	s_min_u32 s4, s4, s5
	v_readfirstlane_b32 s5, v24
	s_min_u32 s4, s4, s5
	v_readfirstlane_b32 s5, v25
	s_min_u32 s4, s4, s5
	v_readfirstlane_b32 s5, v26
	s_min_u32 s4, s4, s5
	v_readfirstlane_b32 s5, v27
	s_min_u32 s4, s4, s5
	s_cmp_lt_u32 s4, 32
	s_cbranch_scc1 .Lgcv_poll

.Lgcv_done:
	v_readlane_b32 s0, v254, 8
	v_readlane_b32 s1, v254, 9
	s_add_u32 s34, s0, 0xa00000
	s_addc_u32 s35, s1, 0
	s_add_u32 s36, s0, 0xc00000
	v_readlane_b32 s2, v254, 10
	s_addc_u32 s37, s1, 0
	v_readlane_b32 s3, v254, 11
	s_add_u32 s2, s0, 0xc000000
	s_addc_u32 s3, s1, 0
	s_add_u32 s26, s0, 0xe000000
	s_addc_u32 s27, s1, 0
	s_add_u32 s12, s0, 0xf800000
	v_writelane_b32 v254, s2, 56
	s_addc_u32 s13, s1, 0
	s_waitcnt lgkmcnt(0)
	v_writelane_b32 v254, s3, 57
	s_add_u32 s2, s0, 0x10800000
	s_addc_u32 s3, s1, 0
	v_writelane_b32 v254, s2, 58
	s_add_u32 s30, s0, 0xe00000
	s_addc_u32 s31, s1, 0
	v_writelane_b32 v254, s3, 59
	v_writelane_b32 v254, s58, 60
	s_add_u32 s24, s0, 0xf00000
	s_barrier
	v_writelane_b32 v254, s59, 61
	v_writelane_b32 v254, s61, 62
	v_writelane_b32 v254, s62, 63
	s_addc_u32 s25, s1, 0
	v_mbcnt_lo_u32_b32 v0, -1, 0
	v_mbcnt_hi_u32_b32 v0, -1, v0
	v_writelane_b32 v255, s60, 0
	v_or_b32_e32 v14, s89, v0
	v_writelane_b32 v254, s76, 36
	s_cmpk_lt_i32 s86, 0x480
	v_writelane_b32 v255, s73, 1
	v_readfirstlane_b32 s9, v14
	v_writelane_b32 v254, s77, 37
	s_cbranch_scc0 .LBB0_790
	s_movk_i32 s29, 0x91
	s_and_b64 s[0:1], s[22:23], exec
	v_lshlrev_b32_e32 v0, 4, v14
	s_cselect_b32 s0, s29, 0x90
	v_add_u32_e32 v1, 0x2000, v0
	s_mul_i32 s0, s0, s62
	v_ashrrev_i32_e32 v2, 31, v1
	s_add_i32 s0, s0, s61
	v_lshrrev_b32_e32 v2, 22, v2
	s_mul_hi_i32 s1, s0, 0x38e38e39
	v_add_u32_e32 v2, v1, v2
	s_lshr_b32 s2, s1, 31
	s_ashr_i32 s1, s1, 4
	v_ashrrev_i32_e32 v8, 10, v2
	s_add_i32 s1, s1, s2
	v_mul_i32_i24_e32 v2, 0x400, v8
	s_lshl_b32 s2, s1, 3
	s_mulk_i32 s1, 0x48
	v_sub_u32_e32 v1, v1, v2
	s_sub_i32 s0, s0, s1
	v_lshrrev_b32_e32 v2, 4, v1
	s_bfe_i32 s1, s0, 0x80000
	v_bitop3_b32 v1, v2, v1, 32 bitop3:0x6c
	s_bfe_u32 s1, s1, 0x3000c
	v_ashrrev_i32_e32 v2, 31, v1
	s_add_i32 s1, s0, s1
	v_lshrrev_b32_e32 v2, 26, v2
	s_bfe_i32 s3, s1, 0x80000
	s_and_b32 s1, s1, 0xf8
	v_add_u32_e32 v2, v1, v2
	v_lshlrev_b32_e32 v3, 3, v8
	s_sub_i32 s0, s0, s1
	v_ashrrev_i32_e32 v9, 6, v2
	v_and_b32_e32 v3, -16, v3
	s_sext_i32_i8 s0, s0
	v_add_u32_e32 v3, v9, v3
	s_add_i32 s2, s2, s0
	v_and_b32_e32 v4, 3, v9
	s_mov_b32 s0, 0x1fffe0
	v_lshrrev_b32_e32 v5, 2, v3
	v_lshlrev_b32_e32 v6, 1, v3
	v_and_b32_e32 v2, 0xc0, v2
	v_and_or_b32 v4, v3, s0, v4
	v_and_b32_e32 v5, 4, v5
	v_and_b32_e32 v6, 24, v6
	v_sub_u32_e32 v1, v1, v2
	v_mov_b32_e32 v2, 1
	v_or3_b32 v4, v4, v5, v6
	v_lshlrev_b32_e32 v5, 5, v8
	v_ashrrev_i16_sdwa v1, v2, sext(v1) dst_sel:DWORD dst_unused:UNUSED_PAD src0_sel:DWORD src1_sel:BYTE_0
	v_and_b32_e32 v5, 32, v5
	v_bfe_i32 v10, v1, 0, 16
	v_add_lshl_u32 v1, v5, v10, 1
	v_lshl_add_u32 v152, v4, 11, v1
	v_lshl_add_u32 v154, v3, 11, v1
	v_bfe_i32 v1, v14, 27, 1
	v_lshrrev_b32_e32 v1, 22, v1
	v_add_u32_e32 v1, v0, v1
	v_and_b32_e32 v1, 0xfffffc00, v1
	v_sub_u32_e32 v0, v0, v1
	v_lshrrev_b32_e32 v1, 4, v0
	v_ashrrev_i32_e32 v3, 31, v14
	v_bitop3_b32 v0, v1, v0, 32 bitop3:0x6c
	v_lshrrev_b32_e32 v3, 26, v3
	v_ashrrev_i32_e32 v1, 31, v0
	v_add_u32_e32 v3, v14, v3
	v_lshrrev_b32_e32 v1, 26, v1
	v_ashrrev_i32_e32 v12, 6, v3
	v_add_u32_e32 v1, v0, v1
	v_lshlrev_b32_e32 v3, 3, v12
	v_ashrrev_i32_e32 v11, 6, v1
	v_and_b32_e32 v3, -16, v3
	s_sext_i32_i16 s3, s3
	v_add_u32_e32 v3, v11, v3
	s_lshr_b32 s8, s3, 3
	v_and_b32_e32 v4, 3, v11
	v_lshrrev_b32_e32 v5, 2, v3
	v_lshlrev_b32_e32 v6, 1, v3
	v_and_b32_e32 v1, 0xc0, v1
	s_ashr_i32 s14, s9, 6
	v_and_or_b32 v4, v3, s0, v4
	v_and_b32_e32 v5, 4, v5
	v_and_b32_e32 v6, 24, v6
	v_sub_u32_e32 v0, v0, v1
	s_ashr_i32 s3, s2, 31
	s_bfe_i64 s[4:5], s[8:9], 0x100000
	s_ashr_i32 s11, s9, 8
	s_lshl_b32 s33, s14, 10
	v_or3_b32 v4, v4, v5, v6
	v_lshlrev_b32_e32 v5, 5, v12
	v_ashrrev_i16_sdwa v0, v2, sext(v0) dst_sel:DWORD dst_unused:UNUSED_PAD src0_sel:DWORD src1_sel:BYTE_0
	s_lshl_b64 s[0:1], s[2:3], 19
	s_lshl_b64 s[4:5], s[4:5], 19
	v_and_b32_e32 v5, 32, v5
	v_bfe_i32 v13, v0, 0, 16
	s_add_u32 s6, s20, s4
	v_add_lshl_u32 v0, v5, v13, 1
	s_addc_u32 s7, s21, s5
	s_add_i32 s64, s33, 0
	v_lshl_add_u32 v156, v4, 11, v0
	s_add_i32 m0, s64, 0x10000
	v_lshl_add_u32 v158, v3, 11, v0
	global_load_lds_dwordx4 v156, s[6:7]
	s_add_i32 m0, s64, 0x12000
	s_add_u32 s4, s6, 0x40000
	global_load_lds_dwordx4 v152, s[6:7]
	s_addc_u32 s5, s7, 0
	s_add_i32 m0, s64, 0x14000
	v_mov_b32_e32 v157, 0
	global_load_lds_dwordx4 v156, s[4:5]
	s_add_i32 m0, s64, 0x16000
	v_writelane_b32 v254, s78, 30
	global_load_lds_dwordx4 v152, s[4:5]
	s_add_u32 s4, s76, s0
	s_addc_u32 s5, s77, s1
	s_add_i32 s65, s64, 0x2000
	s_mov_b32 m0, s64
	s_add_u32 s0, s4, 0x40000
	global_load_lds_dwordx4 v158, s[4:5]
	s_mov_b32 m0, s65
	s_addc_u32 s1, s5, 0
	s_add_i32 s66, s64, 0x4000
	global_load_lds_dwordx4 v154, s[4:5]
	s_mov_b32 m0, s66
	s_add_i32 s67, s64, 0x6000
	global_load_lds_dwordx4 v158, s[0:1]
	s_mov_b32 m0, s67
	v_mov_b32_e32 v153, v157
	global_load_lds_dwordx4 v154, s[0:1]
	v_mov_b32_e32 v159, v157
	v_mov_b32_e32 v155, v157
	s_cmp_eq_u32 s11, 1
	v_writelane_b32 v254, s79, 31
	s_mov_b64 s[94:95], s[74:75]
	s_mov_b64 s[92:93], s[70:71]
	s_mov_b32 s91, s72
	s_mov_b32 s70, 0
	v_lshl_add_u64 v[6:7], s[6:7], 0, v[156:157]
	v_lshl_add_u64 v[4:5], s[6:7], 0, v[152:153]
	v_lshl_add_u64 v[0:1], s[4:5], 0, v[158:159]
	s_cselect_b64 s[0:1], -1, 0
	s_cmp_lg_u32 s11, 1
	v_lshl_add_u64 v[2:3], s[4:5], 0, v[154:155]
	s_cbranch_scc1 .LBB0_698
	s_barrier
